# K-loops: the redundant s_waitcnt lgkmcnt(0) right after each phase barrier replaced by s_nop 0 (same size, code placement unchanged)
# baseline (speedup 1.0000x reference)
; #define PG8_STAGE(bufoff, gbase, voff) do { _Pragma("unroll") for (int _i = 0; _i < 2; ++_i) \
;         __builtin_amdgcn_global_load_lds((const unsigned*)((const char*)(gbase) + (voff)[_i]), (LAS unsigned*)(lds + (bufoff) + ldsw + _i * 8192), 16, 0, 0); } while (0)
; #define PG8_LDA(dst, b, h) do { _Pragma("unroll") for (int m = 0; m < 4; ++m) _Pragma("unroll") for (int k = 0; k < 2; ++k) dst[m][k] = *(const LAS bf16x8*)(lds + PG8_SA(b, h) + aoff + m * 2048 + k * 1024); } while (0)
; #define PG8_LDB(dst, b, h) do { _Pragma("unroll") for (int n = 0; n < 2; ++n) _Pragma("unroll") for (int k = 0; k < 2; ++k) dst[n][k] = *(const LAS bf16x8*)(lds + PG8_SB(b, h) + boff + n * 2048 + k * 1024); } while (0)
; #define PG8_MMA(ai, bj, At, Bt) do { __builtin_amdgcn_s_setprio(1); _Pragma("unroll") for (int m = 0; m < 4; ++m) _Pragma("unroll") for (int n = 0; n < 2; ++n) _Pragma("unroll") for (int k = 0; k < 2; ++k) \
;         acc[ai][bj][m][n] = __builtin_amdgcn_mfma_f32_16x16x32_bf16(Bt[n][k], At[m][k], acc[ai][bj][m][n], 0, 0, 0); __builtin_amdgcn_s_setprio(0); } while (0)
; #define PG8_WAIT_V(n) asm volatile("s_waitcnt vmcnt(" #n ")" ::: "memory")
; #define PG8_WAIT_L(n) asm volatile("s_waitcnt lgkmcnt(" #n ")" ::: "memory")
; #define PG8_BAR __builtin_amdgcn_s_barrier()
; #define PG8_SCHED __builtin_amdgcn_sched_barrier(0)
; template <class Epi>
; __device__ __forceinline__ void gemm_phase(LAS unsigned char* lds, const Gemm g, const StaticOrder& S, const Epi& E, const float* SS) {
;     ...
;         for (int t = 0; t < nt; t += 2) {
;             const bool last = (t == nt - 2);
;             const char* a1 = cA + (size_t)(t + 1) * kstep;
;             const char* a2 = last ? nA : cA + (size_t)(t + 2) * kstep; const char* b2 = last ? nB : cB + (size_t)(t + 2) * kstep;
;             const char* a3 = a2 + kstep; const char* b3 = b2 + kstep;
;             PG8_LDB(B0, 0, 0); PG8_LDB(B1, 0, 1); PG8_SCHED; PG8_LDA(At, 0, 0); PG8_STAGE(PG8_SA(1, 1), a1 + hstep, voffA);
;             PG8_WAIT_V(8); PG8_WAIT_L(0); PG8_BAR; PG8_MMA(0, 0, At, B0); PG8_MMA(0, 1, At, B1); PG8_BAR; PG8_SCHED;
;             PG8_LDA(At, 0, 1); PG8_STAGE(PG8_SB(0, 0), b2, voffB); PG8_STAGE(PG8_SB(0, 1), b2 + hstep, voffB); PG8_STAGE(PG8_SA(0, 0), a2, voffA);
;             PG8_WAIT_V(8); PG8_WAIT_L(0); PG8_BAR; PG8_MMA(1, 0, At, B0); PG8_MMA(1, 1, At, B1); PG8_BAR; PG8_SCHED;
.LBB0_380:
	s_add_u32 s36, s18, s34
	s_addc_u32 s37, s19, s35
	s_add_u32 s36, s36, 0x100
	s_addc_u32 s37, s37, 0
	s_add_u32 s52, s4, s34
	s_addc_u32 s53, s5, s35
	s_add_i32 s54, 0, 0x10000
	s_cmpk_eq_i32 s34, 0x700
	s_cselect_b32 s39, s27, s37
	s_cselect_b32 s38, s49, s36
	s_cselect_b32 s37, s25, s53
	s_cselect_b32 s36, s50, s52
	s_add_i32 s55, 0, 0x14000
	v_add_u32_e32 v168, s54, v145
	v_add_u32_e32 v184, s55, v145
	ds_read_b128 v[156:159], v168
	ds_read_b128 v[160:163], v168 offset:1024
	ds_read_b128 v[164:167], v168 offset:2048
	ds_read_b128 v[168:171], v168 offset:3072
	ds_read_b128 v[172:175], v184
	ds_read_b128 v[176:179], v184 offset:1024
	ds_read_b128 v[180:183], v184 offset:2048
	ds_read_b128 v[184:187], v184 offset:3072
	v_lshl_add_u64 v[196:197], v[142:143], 0, s[34:35]
	s_add_i32 m0, s15, 0xc000
	ds_read_b128 v[188:191], v155
	ds_read_b128 v[192:195], v155 offset:1024
	ds_read_b128 v[200:203], v155 offset:2048
	ds_read_b128 v[204:207], v155 offset:3072
	ds_read_b128 v[216:219], v155 offset:4096
	ds_read_b128 v[220:223], v155 offset:5120
	ds_read_b128 v[224:227], v155 offset:6144
	ds_read_b128 v[228:231], v155 offset:7168
	global_load_lds_dwordx4 v[196:197], off
	v_lshl_add_u64 v[196:197], v[140:141], 0, s[34:35]
	s_add_i32 m0, s15, 0xe000
	s_nop 0
	global_load_lds_dwordx4 v[196:197], off
	s_waitcnt vmcnt(8)
	s_waitcnt lgkmcnt(0)
	s_barrier
	s_nop 0
	v_mfma_f32_16x16x32_bf16 v[94:97], v[156:159], v[188:191], v[94:97]
	v_mfma_f32_16x16x32_bf16 v[90:93], v[164:167], v[188:191], v[90:93]
	v_mfma_f32_16x16x32_bf16 v[86:89], v[156:159], v[200:203], v[86:89]
	v_mfma_f32_16x16x32_bf16 v[82:85], v[164:167], v[200:203], v[82:85]
	v_mfma_f32_16x16x32_bf16 v[78:81], v[156:159], v[216:219], v[78:81]
	v_mfma_f32_16x16x32_bf16 v[74:77], v[164:167], v[216:219], v[74:77]
	v_mfma_f32_16x16x32_bf16 v[70:73], v[156:159], v[224:227], v[70:73]
	v_mfma_f32_16x16x32_bf16 v[66:69], v[164:167], v[224:227], v[66:69]
	v_mfma_f32_16x16x32_bf16 v[94:97], v[160:163], v[192:195], v[94:97]
	v_mfma_f32_16x16x32_bf16 v[90:93], v[168:171], v[192:195], v[90:93]
	v_mfma_f32_16x16x32_bf16 v[86:89], v[160:163], v[204:207], v[86:89]
	v_mfma_f32_16x16x32_bf16 v[82:85], v[168:171], v[204:207], v[82:85]
	v_mfma_f32_16x16x32_bf16 v[78:81], v[160:163], v[220:223], v[78:81]
	v_mfma_f32_16x16x32_bf16 v[74:77], v[168:171], v[220:223], v[74:77]
	v_mfma_f32_16x16x32_bf16 v[70:73], v[160:163], v[228:231], v[70:73]
	v_mfma_f32_16x16x32_bf16 v[66:69], v[168:171], v[228:231], v[66:69]
	v_mfma_f32_16x16x32_bf16 v[62:65], v[172:175], v[188:191], v[62:65]
	v_mfma_f32_16x16x32_bf16 v[58:61], v[180:183], v[188:191], v[58:61]
	v_mfma_f32_16x16x32_bf16 v[54:57], v[172:175], v[200:203], v[54:57]
	v_mfma_f32_16x16x32_bf16 v[50:53], v[180:183], v[200:203], v[50:53]
	v_mfma_f32_16x16x32_bf16 v[46:49], v[172:175], v[216:219], v[46:49]
	v_mfma_f32_16x16x32_bf16 v[42:45], v[180:183], v[216:219], v[42:45]
	v_mfma_f32_16x16x32_bf16 v[38:41], v[172:175], v[224:227], v[38:41]
	v_mfma_f32_16x16x32_bf16 v[34:37], v[180:183], v[224:227], v[34:37]
	v_mfma_f32_16x16x32_bf16 v[62:65], v[176:179], v[192:195], v[62:65]
	v_mfma_f32_16x16x32_bf16 v[58:61], v[184:187], v[192:195], v[58:61]
	v_mfma_f32_16x16x32_bf16 v[54:57], v[176:179], v[204:207], v[54:57]
	v_mfma_f32_16x16x32_bf16 v[50:53], v[184:187], v[204:207], v[50:53]
	v_mfma_f32_16x16x32_bf16 v[46:49], v[176:179], v[220:223], v[46:49]
	v_mfma_f32_16x16x32_bf16 v[42:45], v[184:187], v[220:223], v[42:45]
	v_mfma_f32_16x16x32_bf16 v[38:41], v[176:179], v[228:231], v[38:41]
	v_mfma_f32_16x16x32_bf16 v[34:37], v[184:187], v[228:231], v[34:37]
	s_barrier
	s_add_i32 s52, s54, s41
	v_lshl_add_u64 v[196:197], s[36:37], 0, v[0:1]
	s_mov_b32 m0, s52
	ds_read_b128 v[188:191], v155 offset:16384
	ds_read_b128 v[192:195], v155 offset:17408
	ds_read_b128 v[200:203], v155 offset:18432
	ds_read_b128 v[204:207], v155 offset:19456
	ds_read_b128 v[216:219], v155 offset:20480
	ds_read_b128 v[220:223], v155 offset:21504
	ds_read_b128 v[224:227], v155 offset:22528
	ds_read_b128 v[228:231], v155 offset:23552
	global_load_lds_dwordx4 v[196:197], off
	s_add_i32 m0, s52, 0x2000
	s_add_u32 s52, s36, 0x40000
	v_lshl_add_u64 v[232:233], s[36:37], 0, v[134:135]
	s_addc_u32 s53, s37, 0
	s_add_i32 s54, s55, s41
	global_load_lds_dwordx4 v[232:233], off
	v_lshl_add_u64 v[234:235], s[52:53], 0, v[0:1]
	s_mov_b32 m0, s54
	v_lshl_add_u64 v[236:237], s[38:39], 0, v[132:133]
	global_load_lds_dwordx4 v[234:235], off
	v_lshl_add_u64 v[234:235], s[52:53], 0, v[134:135]
	s_add_i32 m0, s54, 0x2000
	s_nop 0
	global_load_lds_dwordx4 v[234:235], off
	v_lshl_add_u64 v[234:235], s[38:39], 0, v[130:131]
	s_mov_b32 m0, s15
	s_nop 0
	global_load_lds_dwordx4 v[234:235], off
	s_mov_b32 m0, s17
	s_nop 0
	global_load_lds_dwordx4 v[236:237], off
	s_waitcnt vmcnt(8)
	s_waitcnt lgkmcnt(0)
	s_barrier
; #define PG8_STAGE(bufoff, gbase, voff) do { _Pragma("unroll") for (int _i = 0; _i < 2; ++_i) \
;         __builtin_amdgcn_global_load_lds((const unsigned*)((const char*)(gbase) + (voff)[_i]), (LAS unsigned*)(lds + (bufoff) + ldsw + _i * 8192), 16, 0, 0); } while (0)
; #define PG8_LDA(dst, b, h) do { _Pragma("unroll") for (int m = 0; m < 4; ++m) _Pragma("unroll") for (int k = 0; k < 2; ++k) dst[m][k] = *(const LAS bf16x8*)(lds + PG8_SA(b, h) + aoff + m * 2048 + k * 1024); } while (0)
; #define PG8_LDB(dst, b, h) do { _Pragma("unroll") for (int n = 0; n < 2; ++n) _Pragma("unroll") for (int k = 0; k < 2; ++k) dst[n][k] = *(const LAS bf16x8*)(lds + PG8_SB(b, h) + boff + n * 2048 + k * 1024); } while (0)
; #define PG8_MMA(ai, bj, At, Bt) do { __builtin_amdgcn_s_setprio(1); _Pragma("unroll") for (int m = 0; m < 4; ++m) _Pragma("unroll") for (int n = 0; n < 2; ++n) _Pragma("unroll") for (int k = 0; k < 2; ++k) \
;         acc[ai][bj][m][n] = __builtin_amdgcn_mfma_f32_16x16x32_bf16(Bt[n][k], At[m][k], acc[ai][bj][m][n], 0, 0, 0); __builtin_amdgcn_s_setprio(0); } while (0)
; #define PG8_WAIT_V(n) asm volatile("s_waitcnt vmcnt(" #n ")" ::: "memory")
; #define PG8_WAIT_L(n) asm volatile("s_waitcnt lgkmcnt(" #n ")" ::: "memory")
; #define PG8_BAR __builtin_amdgcn_s_barrier()
; #define PG8_SCHED __builtin_amdgcn_sched_barrier(0)
; template <class Epi>
; __device__ __forceinline__ void gemm_phase(LAS unsigned char* lds, const Gemm g, const StaticOrder& S, const Epi& E, const float* SS) {
;     ...
;             PG8_WAIT_V(8); PG8_WAIT_L(0); PG8_BAR; PG8_MMA(1, 0, At, B0); PG8_MMA(1, 1, At, B1); PG8_BAR; PG8_SCHED;
;             PG8_LDB(B0, 1, 0); PG8_LDB(B1, 1, 1); PG8_SCHED; PG8_LDA(At, 1, 0); PG8_STAGE(PG8_SA(0, 1), a2 + hstep, voffA);
;             PG8_WAIT_V(8); PG8_WAIT_L(0); PG8_BAR; PG8_MMA(0, 0, At, B0); PG8_MMA(0, 1, At, B1); PG8_BAR; PG8_SCHED;
;             PG8_LDA(At, 1, 1); PG8_STAGE(PG8_SB(1, 0), b3, voffB); PG8_STAGE(PG8_SB(1, 1), b3 + hstep, voffB); PG8_STAGE(PG8_SA(1, 0), a3, voffA);
	s_nop 0
	v_mfma_f32_16x16x32_bf16 v[30:33], v[156:159], v[188:191], v[30:33]
	v_mfma_f32_16x16x32_bf16 v[26:29], v[164:167], v[188:191], v[26:29]
	v_mfma_f32_16x16x32_bf16 v[22:25], v[156:159], v[200:203], v[22:25]
	v_mfma_f32_16x16x32_bf16 v[18:21], v[164:167], v[200:203], v[18:21]
	v_mfma_f32_16x16x32_bf16 v[14:17], v[156:159], v[216:219], v[14:17]
	v_mfma_f32_16x16x32_bf16 v[10:13], v[164:167], v[216:219], v[10:13]
	v_mfma_f32_16x16x32_bf16 v[6:9], v[156:159], v[224:227], v[6:9]
	v_mfma_f32_16x16x32_bf16 v[2:5], v[164:167], v[224:227], v[2:5]
	v_mfma_f32_16x16x32_bf16 v[30:33], v[160:163], v[192:195], v[30:33]
	v_mfma_f32_16x16x32_bf16 v[26:29], v[168:171], v[192:195], v[26:29]
	v_mfma_f32_16x16x32_bf16 v[22:25], v[160:163], v[204:207], v[22:25]
	v_mfma_f32_16x16x32_bf16 v[18:21], v[168:171], v[204:207], v[18:21]
	v_mfma_f32_16x16x32_bf16 v[14:17], v[160:163], v[220:223], v[14:17]
	v_mfma_f32_16x16x32_bf16 v[10:13], v[168:171], v[220:223], v[10:13]
	v_mfma_f32_16x16x32_bf16 v[6:9], v[160:163], v[228:231], v[6:9]
	v_mfma_f32_16x16x32_bf16 v[2:5], v[168:171], v[228:231], v[2:5]
	v_mfma_f32_16x16x32_bf16 v[98:101], v[172:175], v[188:191], v[98:101]
	v_mfma_f32_16x16x32_bf16 v[102:105], v[180:183], v[188:191], v[102:105]
	v_mfma_f32_16x16x32_bf16 v[106:109], v[172:175], v[200:203], v[106:109]
	v_mfma_f32_16x16x32_bf16 v[110:113], v[180:183], v[200:203], v[110:113]
	v_mfma_f32_16x16x32_bf16 v[114:117], v[172:175], v[216:219], v[114:117]
	v_mfma_f32_16x16x32_bf16 v[118:121], v[180:183], v[216:219], v[118:121]
	v_mfma_f32_16x16x32_bf16 v[122:125], v[172:175], v[224:227], v[122:125]
	v_mfma_f32_16x16x32_bf16 v[126:129], v[180:183], v[224:227], v[126:129]
	v_mfma_f32_16x16x32_bf16 v[98:101], v[176:179], v[192:195], v[98:101]
	v_mfma_f32_16x16x32_bf16 v[102:105], v[184:187], v[192:195], v[102:105]
	v_mfma_f32_16x16x32_bf16 v[106:109], v[176:179], v[204:207], v[106:109]
	v_mfma_f32_16x16x32_bf16 v[110:113], v[184:187], v[204:207], v[110:113]
	v_mfma_f32_16x16x32_bf16 v[114:117], v[176:179], v[220:223], v[114:117]
	v_mfma_f32_16x16x32_bf16 v[118:121], v[184:187], v[220:223], v[118:121]
	v_mfma_f32_16x16x32_bf16 v[122:125], v[176:179], v[228:231], v[122:125]
	v_mfma_f32_16x16x32_bf16 v[126:129], v[184:187], v[228:231], v[126:129]
	s_barrier
	s_add_i32 s52, 0, 0x18000
	s_add_i32 s53, 0, 0x1c000
	v_add_u32_e32 v168, s52, v145
	v_add_u32_e32 v184, s53, v145
	ds_read_b128 v[156:159], v168
	ds_read_b128 v[160:163], v168 offset:1024
	ds_read_b128 v[164:167], v168 offset:2048
	ds_read_b128 v[168:171], v168 offset:3072
	ds_read_b128 v[172:175], v184
	ds_read_b128 v[176:179], v184 offset:1024
	ds_read_b128 v[180:183], v184 offset:2048
	ds_read_b128 v[184:187], v184 offset:3072
	s_add_u32 s38, s38, 0x40000
	s_addc_u32 s39, s39, 0
	s_mov_b32 m0, s42
	v_lshl_add_u64 v[238:239], s[38:39], 0, v[130:131]
	ds_read_b128 v[188:191], v155 offset:32768
	ds_read_b128 v[192:195], v155 offset:33792
	ds_read_b128 v[200:203], v155 offset:34816
	ds_read_b128 v[204:207], v155 offset:35840
	ds_read_b128 v[216:219], v155 offset:36864
	ds_read_b128 v[220:223], v155 offset:37888
	ds_read_b128 v[224:227], v155 offset:38912
	ds_read_b128 v[228:231], v155 offset:39936
	global_load_lds_dwordx4 v[238:239], off
	v_lshl_add_u64 v[238:239], s[38:39], 0, v[132:133]
	s_mov_b32 m0, s43
	s_nop 0
	global_load_lds_dwordx4 v[238:239], off
	s_waitcnt vmcnt(8)
	s_waitcnt lgkmcnt(0)
	s_barrier
	s_nop 0
	v_mfma_f32_16x16x32_bf16 v[94:97], v[156:159], v[188:191], v[94:97]
	v_mfma_f32_16x16x32_bf16 v[90:93], v[164:167], v[188:191], v[90:93]
	v_mfma_f32_16x16x32_bf16 v[86:89], v[156:159], v[200:203], v[86:89]
	v_mfma_f32_16x16x32_bf16 v[82:85], v[164:167], v[200:203], v[82:85]
	v_mfma_f32_16x16x32_bf16 v[78:81], v[156:159], v[216:219], v[78:81]
	v_mfma_f32_16x16x32_bf16 v[74:77], v[164:167], v[216:219], v[74:77]
	v_mfma_f32_16x16x32_bf16 v[70:73], v[156:159], v[224:227], v[70:73]
	v_mfma_f32_16x16x32_bf16 v[66:69], v[164:167], v[224:227], v[66:69]
	v_mfma_f32_16x16x32_bf16 v[94:97], v[160:163], v[192:195], v[94:97]
	v_mfma_f32_16x16x32_bf16 v[90:93], v[168:171], v[192:195], v[90:93]
	v_mfma_f32_16x16x32_bf16 v[86:89], v[160:163], v[204:207], v[86:89]
	v_mfma_f32_16x16x32_bf16 v[82:85], v[168:171], v[204:207], v[82:85]
	v_mfma_f32_16x16x32_bf16 v[78:81], v[160:163], v[220:223], v[78:81]
	v_mfma_f32_16x16x32_bf16 v[74:77], v[168:171], v[220:223], v[74:77]
	v_mfma_f32_16x16x32_bf16 v[70:73], v[160:163], v[228:231], v[70:73]
	v_mfma_f32_16x16x32_bf16 v[66:69], v[168:171], v[228:231], v[66:69]
	v_mfma_f32_16x16x32_bf16 v[62:65], v[172:175], v[188:191], v[62:65]
	v_mfma_f32_16x16x32_bf16 v[58:61], v[180:183], v[188:191], v[58:61]
	v_mfma_f32_16x16x32_bf16 v[54:57], v[172:175], v[200:203], v[54:57]
	v_mfma_f32_16x16x32_bf16 v[50:53], v[180:183], v[200:203], v[50:53]
	v_mfma_f32_16x16x32_bf16 v[46:49], v[172:175], v[216:219], v[46:49]
	v_mfma_f32_16x16x32_bf16 v[42:45], v[180:183], v[216:219], v[42:45]
	v_mfma_f32_16x16x32_bf16 v[38:41], v[172:175], v[224:227], v[38:41]
	v_mfma_f32_16x16x32_bf16 v[34:37], v[180:183], v[224:227], v[34:37]
	v_mfma_f32_16x16x32_bf16 v[62:65], v[176:179], v[192:195], v[62:65]
	v_mfma_f32_16x16x32_bf16 v[58:61], v[184:187], v[192:195], v[58:61]
	v_mfma_f32_16x16x32_bf16 v[54:57], v[176:179], v[204:207], v[54:57]
	v_mfma_f32_16x16x32_bf16 v[50:53], v[184:187], v[204:207], v[50:53]
	v_mfma_f32_16x16x32_bf16 v[46:49], v[176:179], v[220:223], v[46:49]
	v_mfma_f32_16x16x32_bf16 v[42:45], v[184:187], v[220:223], v[42:45]
	v_mfma_f32_16x16x32_bf16 v[38:41], v[176:179], v[228:231], v[38:41]
	v_mfma_f32_16x16x32_bf16 v[34:37], v[184:187], v[228:231], v[34:37]
	s_barrier
; #define PG8_STAGE(bufoff, gbase, voff) do { _Pragma("unroll") for (int _i = 0; _i < 2; ++_i) \
;         __builtin_amdgcn_global_load_lds((const unsigned*)((const char*)(gbase) + (voff)[_i]), (LAS unsigned*)(lds + (bufoff) + ldsw + _i * 8192), 16, 0, 0); } while (0)
; #define PG8_LDA(dst, b, h) do { _Pragma("unroll") for (int m = 0; m < 4; ++m) _Pragma("unroll") for (int k = 0; k < 2; ++k) dst[m][k] = *(const LAS bf16x8*)(lds + PG8_SA(b, h) + aoff + m * 2048 + k * 1024); } while (0)
; #define PG8_MMA(ai, bj, At, Bt) do { __builtin_amdgcn_s_setprio(1); _Pragma("unroll") for (int m = 0; m < 4; ++m) _Pragma("unroll") for (int n = 0; n < 2; ++n) _Pragma("unroll") for (int k = 0; k < 2; ++k) \
;         acc[ai][bj][m][n] = __builtin_amdgcn_mfma_f32_16x16x32_bf16(Bt[n][k], At[m][k], acc[ai][bj][m][n], 0, 0, 0); __builtin_amdgcn_s_setprio(0); } while (0)
; #define PG8_WAIT_V(n) asm volatile("s_waitcnt vmcnt(" #n ")" ::: "memory")
; #define PG8_WAIT_L(n) asm volatile("s_waitcnt lgkmcnt(" #n ")" ::: "memory")
; #define PG8_BAR __builtin_amdgcn_s_barrier()
; #define PG8_SCHED __builtin_amdgcn_sched_barrier(0)
; template <class Epi>
; __device__ __forceinline__ void gemm_phase(LAS unsigned char* lds, const Gemm g, const StaticOrder& S, const Epi& E, const float* SS) {
;     ...
;             PG8_LDA(At, 1, 1); PG8_STAGE(PG8_SB(1, 0), b3, voffB); PG8_STAGE(PG8_SB(1, 1), b3 + hstep, voffB); PG8_STAGE(PG8_SA(1, 0), a3, voffA);
;             PG8_WAIT_V(8); PG8_WAIT_L(0); PG8_BAR; PG8_MMA(1, 0, At, B0); PG8_MMA(1, 1, At, B1); PG8_BAR; PG8_SCHED;
;         }
;         if (wr == 0) PG8_BAR;
	s_add_i32 s38, s52, s41
	v_lshl_add_u64 v[196:197], v[196:197], 0, s[64:65]
	s_mov_b32 m0, s38
	ds_read_b128 v[188:191], v155 offset:49152
	ds_read_b128 v[192:195], v155 offset:50176
	ds_read_b128 v[200:203], v155 offset:51200
	ds_read_b128 v[204:207], v155 offset:52224
	ds_read_b128 v[216:219], v155 offset:53248
	ds_read_b128 v[220:223], v155 offset:54272
	ds_read_b128 v[224:227], v155 offset:55296
	ds_read_b128 v[228:231], v155 offset:56320
	global_load_lds_dwordx4 v[196:197], off
	s_add_i32 m0, s38, 0x2000
	s_add_u32 s36, s36, 0x40080
	v_lshl_add_u64 v[196:197], v[232:233], 0, s[64:65]
	s_addc_u32 s37, s37, 0
	s_add_i32 s38, s53, s41
	global_load_lds_dwordx4 v[196:197], off
	v_lshl_add_u64 v[196:197], s[36:37], 0, v[0:1]
	s_mov_b32 m0, s38
	s_nop 0
	global_load_lds_dwordx4 v[196:197], off
	v_lshl_add_u64 v[196:197], s[36:37], 0, v[134:135]
	s_add_i32 m0, s38, 0x2000
	s_nop 0
	global_load_lds_dwordx4 v[196:197], off
	v_lshl_add_u64 v[196:197], v[234:235], 0, s[64:65]
	s_mov_b32 m0, s12
	s_nop 0
	global_load_lds_dwordx4 v[196:197], off
	v_lshl_add_u64 v[196:197], v[236:237], 0, s[64:65]
	s_mov_b32 m0, s13
	s_nop 0
	global_load_lds_dwordx4 v[196:197], off
	s_waitcnt vmcnt(8)
	s_waitcnt lgkmcnt(0)
	s_barrier
	s_nop 0
	v_mfma_f32_16x16x32_bf16 v[30:33], v[156:159], v[188:191], v[30:33]
	v_mfma_f32_16x16x32_bf16 v[26:29], v[164:167], v[188:191], v[26:29]
	v_mfma_f32_16x16x32_bf16 v[22:25], v[156:159], v[200:203], v[22:25]
	v_mfma_f32_16x16x32_bf16 v[18:21], v[164:167], v[200:203], v[18:21]
	v_mfma_f32_16x16x32_bf16 v[14:17], v[156:159], v[216:219], v[14:17]
	v_mfma_f32_16x16x32_bf16 v[10:13], v[164:167], v[216:219], v[10:13]
	v_mfma_f32_16x16x32_bf16 v[6:9], v[156:159], v[224:227], v[6:9]
	v_mfma_f32_16x16x32_bf16 v[2:5], v[164:167], v[224:227], v[2:5]
	v_mfma_f32_16x16x32_bf16 v[30:33], v[160:163], v[192:195], v[30:33]
	v_mfma_f32_16x16x32_bf16 v[26:29], v[168:171], v[192:195], v[26:29]
	v_mfma_f32_16x16x32_bf16 v[22:25], v[160:163], v[204:207], v[22:25]
	v_mfma_f32_16x16x32_bf16 v[18:21], v[168:171], v[204:207], v[18:21]
	v_mfma_f32_16x16x32_bf16 v[14:17], v[160:163], v[220:223], v[14:17]
	v_mfma_f32_16x16x32_bf16 v[10:13], v[168:171], v[220:223], v[10:13]
	v_mfma_f32_16x16x32_bf16 v[6:9], v[160:163], v[228:231], v[6:9]
	v_mfma_f32_16x16x32_bf16 v[2:5], v[168:171], v[228:231], v[2:5]
	v_mfma_f32_16x16x32_bf16 v[98:101], v[172:175], v[188:191], v[98:101]
	v_mfma_f32_16x16x32_bf16 v[102:105], v[180:183], v[188:191], v[102:105]
	v_mfma_f32_16x16x32_bf16 v[106:109], v[172:175], v[200:203], v[106:109]
	v_mfma_f32_16x16x32_bf16 v[110:113], v[180:183], v[200:203], v[110:113]
	v_mfma_f32_16x16x32_bf16 v[114:117], v[172:175], v[216:219], v[114:117]
	v_mfma_f32_16x16x32_bf16 v[118:121], v[180:183], v[216:219], v[118:121]
	v_mfma_f32_16x16x32_bf16 v[122:125], v[172:175], v[224:227], v[122:125]
	v_mfma_f32_16x16x32_bf16 v[126:129], v[180:183], v[224:227], v[126:129]
	v_mfma_f32_16x16x32_bf16 v[98:101], v[176:179], v[192:195], v[98:101]
	v_mfma_f32_16x16x32_bf16 v[102:105], v[184:187], v[192:195], v[102:105]
	v_mfma_f32_16x16x32_bf16 v[106:109], v[176:179], v[204:207], v[106:109]
	v_mfma_f32_16x16x32_bf16 v[110:113], v[184:187], v[204:207], v[110:113]
	v_mfma_f32_16x16x32_bf16 v[114:117], v[176:179], v[220:223], v[114:117]
	v_mfma_f32_16x16x32_bf16 v[118:121], v[184:187], v[220:223], v[118:121]
	v_mfma_f32_16x16x32_bf16 v[122:125], v[176:179], v[228:231], v[122:125]
	v_mfma_f32_16x16x32_bf16 v[126:129], v[184:187], v[228:231], v[126:129]
	s_barrier
	s_add_i32 s51, s51, 2
	s_add_u32 s34, s34, 0x100
	s_addc_u32 s35, s35, 0
	s_cmp_gt_u32 s51, 13
	s_cbranch_scc0 .LBB0_380
	s_and_b64 vcc, exec, s[22:23]
	s_cbranch_vccz .LBB0_383
	s_barrier

; #define PG8_STAGE(bufoff, gbase, voff) do { _Pragma("unroll") for (int _i = 0; _i < 2; ++_i) \
;         __builtin_amdgcn_global_load_lds((const unsigned*)((const char*)(gbase) + (voff)[_i]), (LAS unsigned*)(lds + (bufoff) + ldsw + _i * 8192), 16, 0, 0); } while (0)
; #define PG8_LDA(dst, b, h) do { _Pragma("unroll") for (int m = 0; m < 4; ++m) _Pragma("unroll") for (int k = 0; k < 2; ++k) dst[m][k] = *(const LAS bf16x8*)(lds + PG8_SA(b, h) + aoff + m * 2048 + k * 1024); } while (0)
; #define PG8_LDB(dst, b, h) do { _Pragma("unroll") for (int n = 0; n < 2; ++n) _Pragma("unroll") for (int k = 0; k < 2; ++k) dst[n][k] = *(const LAS bf16x8*)(lds + PG8_SB(b, h) + boff + n * 2048 + k * 1024); } while (0)
; #define PG8_MMA(ai, bj, At, Bt) do { __builtin_amdgcn_s_setprio(1); _Pragma("unroll") for (int m = 0; m < 4; ++m) _Pragma("unroll") for (int n = 0; n < 2; ++n) _Pragma("unroll") for (int k = 0; k < 2; ++k) \
;         acc[ai][bj][m][n] = __builtin_amdgcn_mfma_f32_16x16x32_bf16(Bt[n][k], At[m][k], acc[ai][bj][m][n], 0, 0, 0); __builtin_amdgcn_s_setprio(0); } while (0)
; #define PG8_WAIT_V(n) asm volatile("s_waitcnt vmcnt(" #n ")" ::: "memory")
; #define PG8_WAIT_L(n) asm volatile("s_waitcnt lgkmcnt(" #n ")" ::: "memory")
; #define PG8_BAR __builtin_amdgcn_s_barrier()
; #define PG8_SCHED __builtin_amdgcn_sched_barrier(0)
; template <class Epi>
; __device__ __forceinline__ void gemm_phase(LAS unsigned char* lds, const Gemm g, const StaticOrder& S, const Epi& E, const float* SS) {
;     ...
;         for (int t = 0; t < nt; t += 2) {
;             const bool last = (t == nt - 2);
;             const char* a1 = cA + (size_t)(t + 1) * kstep;
;             const char* a2 = last ? nA : cA + (size_t)(t + 2) * kstep; const char* b2 = last ? nB : cB + (size_t)(t + 2) * kstep;
;             const char* a3 = a2 + kstep; const char* b3 = b2 + kstep;
;             PG8_LDB(B0, 0, 0); PG8_LDB(B1, 0, 1); PG8_SCHED; PG8_LDA(At, 0, 0); PG8_STAGE(PG8_SA(1, 1), a1 + hstep, voffA);
;             PG8_WAIT_V(8); PG8_WAIT_L(0); PG8_BAR; PG8_MMA(0, 0, At, B0); PG8_MMA(0, 1, At, B1); PG8_BAR; PG8_SCHED;
;             PG8_LDA(At, 0, 1); PG8_STAGE(PG8_SB(0, 0), b2, voffB); PG8_STAGE(PG8_SB(0, 1), b2 + hstep, voffB); PG8_STAGE(PG8_SA(0, 0), a2, voffA);
;             PG8_WAIT_V(8); PG8_WAIT_L(0); PG8_BAR; PG8_MMA(1, 0, At, B0); PG8_MMA(1, 1, At, B1); PG8_BAR; PG8_SCHED;
.LBB0_501:
	s_add_u32 s60, s40, s58
	s_addc_u32 s61, s41, s59
	s_add_u32 s60, s60, 0x100
	s_addc_u32 s61, s61, 0
	s_add_u32 s86, s4, s58
	s_addc_u32 s87, s5, s59
	s_add_i32 vcc_hi, 0, 0x10000
	s_cmpk_eq_i32 s58, 0x700
	s_cselect_b32 s69, s51, s61
	s_cselect_b32 s68, s52, s60
	v_add_u32_e32 v0, vcc_hi, v167
	s_cselect_b32 s61, s49, s87
	s_cselect_b32 s60, s53, s86
	s_add_i32 s6, 0, 0x14000
	ds_read_b128 v[134:137], v0
	ds_read_b128 v[150:153], v0 offset:1024
	ds_read_b128 v[154:157], v0 offset:2048
	ds_read_b128 v[158:161], v0 offset:3072
	v_add_u32_e32 v0, s6, v167
	ds_read_b128 v[162:165], v0
	ds_read_b128 v[178:181], v0 offset:1024
	ds_read_b128 v[182:185], v0 offset:2048
	ds_read_b128 v[186:189], v0 offset:3072
	v_lshl_add_u64 v[232:233], v[132:133], 0, s[58:59]
	s_add_i32 m0, s37, 0xc000
	ds_read_b128 v[190:193], v177
	ds_read_b128 v[194:197], v177 offset:1024
	ds_read_b128 v[200:203], v177 offset:2048
	ds_read_b128 v[204:207], v177 offset:3072
	ds_read_b128 v[216:219], v177 offset:4096
	ds_read_b128 v[220:223], v177 offset:5120
	ds_read_b128 v[224:227], v177 offset:6144
	ds_read_b128 v[228:231], v177 offset:7168
	global_load_lds_dwordx4 v[232:233], off
	v_lshl_add_u64 v[232:233], v[130:131], 0, s[58:59]
	s_add_i32 m0, s37, 0xe000
	s_nop 0
	global_load_lds_dwordx4 v[232:233], off
	s_waitcnt vmcnt(8)
	s_waitcnt lgkmcnt(0)
	s_barrier
	s_nop 0
	v_mfma_f32_16x16x32_bf16 v[94:97], v[134:137], v[190:193], v[94:97]
	v_mfma_f32_16x16x32_bf16 v[90:93], v[154:157], v[190:193], v[90:93]
	v_mfma_f32_16x16x32_bf16 v[86:89], v[134:137], v[200:203], v[86:89]
	v_mfma_f32_16x16x32_bf16 v[82:85], v[154:157], v[200:203], v[82:85]
	v_mfma_f32_16x16x32_bf16 v[78:81], v[134:137], v[216:219], v[78:81]
	v_mfma_f32_16x16x32_bf16 v[74:77], v[154:157], v[216:219], v[74:77]
	v_mfma_f32_16x16x32_bf16 v[70:73], v[134:137], v[224:227], v[70:73]
	v_mfma_f32_16x16x32_bf16 v[66:69], v[154:157], v[224:227], v[66:69]
	v_mfma_f32_16x16x32_bf16 v[94:97], v[150:153], v[194:197], v[94:97]
	v_mfma_f32_16x16x32_bf16 v[90:93], v[158:161], v[194:197], v[90:93]
	v_mfma_f32_16x16x32_bf16 v[86:89], v[150:153], v[204:207], v[86:89]
	v_mfma_f32_16x16x32_bf16 v[82:85], v[158:161], v[204:207], v[82:85]
	v_mfma_f32_16x16x32_bf16 v[78:81], v[150:153], v[220:223], v[78:81]
	v_mfma_f32_16x16x32_bf16 v[74:77], v[158:161], v[220:223], v[74:77]
	v_mfma_f32_16x16x32_bf16 v[70:73], v[150:153], v[228:231], v[70:73]
	v_mfma_f32_16x16x32_bf16 v[66:69], v[158:161], v[228:231], v[66:69]
	v_mfma_f32_16x16x32_bf16 v[62:65], v[162:165], v[190:193], v[62:65]
	v_mfma_f32_16x16x32_bf16 v[58:61], v[182:185], v[190:193], v[58:61]
	v_mfma_f32_16x16x32_bf16 v[54:57], v[162:165], v[200:203], v[54:57]
	v_mfma_f32_16x16x32_bf16 v[50:53], v[182:185], v[200:203], v[50:53]
	v_mfma_f32_16x16x32_bf16 v[46:49], v[162:165], v[216:219], v[46:49]
	v_mfma_f32_16x16x32_bf16 v[42:45], v[182:185], v[216:219], v[42:45]
	v_mfma_f32_16x16x32_bf16 v[38:41], v[162:165], v[224:227], v[38:41]
	v_mfma_f32_16x16x32_bf16 v[34:37], v[182:185], v[224:227], v[34:37]
	v_mfma_f32_16x16x32_bf16 v[62:65], v[178:181], v[194:197], v[62:65]
	v_mfma_f32_16x16x32_bf16 v[58:61], v[186:189], v[194:197], v[58:61]
	v_mfma_f32_16x16x32_bf16 v[54:57], v[178:181], v[204:207], v[54:57]
	v_mfma_f32_16x16x32_bf16 v[50:53], v[186:189], v[204:207], v[50:53]
	v_mfma_f32_16x16x32_bf16 v[46:49], v[178:181], v[220:223], v[46:49]
	v_mfma_f32_16x16x32_bf16 v[42:45], v[186:189], v[220:223], v[42:45]
	v_mfma_f32_16x16x32_bf16 v[38:41], v[178:181], v[228:231], v[38:41]
	v_mfma_f32_16x16x32_bf16 v[34:37], v[186:189], v[228:231], v[34:37]
	s_barrier
	s_add_i32 s86, vcc_hi, s25
	v_lshl_add_u64 v[232:233], s[60:61], 0, v[140:141]
	s_mov_b32 m0, s86
	ds_read_b128 v[190:193], v177 offset:16384
	ds_read_b128 v[194:197], v177 offset:17408
	ds_read_b128 v[200:203], v177 offset:18432
	ds_read_b128 v[204:207], v177 offset:19456
	ds_read_b128 v[216:219], v177 offset:20480
	ds_read_b128 v[220:223], v177 offset:21504
	ds_read_b128 v[224:227], v177 offset:22528
	ds_read_b128 v[228:231], v177 offset:23552
	global_load_lds_dwordx4 v[232:233], off
	s_add_i32 m0, s86, 0x2000
	s_add_u32 s86, s60, 0x40000
	v_lshl_add_u64 v[234:235], s[60:61], 0, v[144:145]
	s_addc_u32 s87, s61, 0
	s_add_i32 s6, s6, s25
	global_load_lds_dwordx4 v[234:235], off
	v_lshl_add_u64 v[236:237], s[86:87], 0, v[140:141]
	s_mov_b32 m0, s6
	v_lshl_add_u64 v[238:239], s[68:69], 0, v[142:143]
	global_load_lds_dwordx4 v[236:237], off
	v_lshl_add_u64 v[236:237], s[86:87], 0, v[144:145]
	s_add_i32 m0, s6, 0x2000
	s_nop 0
	global_load_lds_dwordx4 v[236:237], off
	v_lshl_add_u64 v[236:237], s[68:69], 0, v[138:139]
	s_mov_b32 m0, s37
	s_nop 0
	global_load_lds_dwordx4 v[236:237], off
	s_mov_b32 m0, s39
	s_nop 0
	global_load_lds_dwordx4 v[238:239], off
	s_waitcnt vmcnt(8)
	s_waitcnt lgkmcnt(0)
	s_barrier
; #define PG8_STAGE(bufoff, gbase, voff) do { _Pragma("unroll") for (int _i = 0; _i < 2; ++_i) \
;         __builtin_amdgcn_global_load_lds((const unsigned*)((const char*)(gbase) + (voff)[_i]), (LAS unsigned*)(lds + (bufoff) + ldsw + _i * 8192), 16, 0, 0); } while (0)
; #define PG8_LDA(dst, b, h) do { _Pragma("unroll") for (int m = 0; m < 4; ++m) _Pragma("unroll") for (int k = 0; k < 2; ++k) dst[m][k] = *(const LAS bf16x8*)(lds + PG8_SA(b, h) + aoff + m * 2048 + k * 1024); } while (0)
; #define PG8_LDB(dst, b, h) do { _Pragma("unroll") for (int n = 0; n < 2; ++n) _Pragma("unroll") for (int k = 0; k < 2; ++k) dst[n][k] = *(const LAS bf16x8*)(lds + PG8_SB(b, h) + boff + n * 2048 + k * 1024); } while (0)
; #define PG8_MMA(ai, bj, At, Bt) do { __builtin_amdgcn_s_setprio(1); _Pragma("unroll") for (int m = 0; m < 4; ++m) _Pragma("unroll") for (int n = 0; n < 2; ++n) _Pragma("unroll") for (int k = 0; k < 2; ++k) \
;         acc[ai][bj][m][n] = __builtin_amdgcn_mfma_f32_16x16x32_bf16(Bt[n][k], At[m][k], acc[ai][bj][m][n], 0, 0, 0); __builtin_amdgcn_s_setprio(0); } while (0)
; #define PG8_WAIT_V(n) asm volatile("s_waitcnt vmcnt(" #n ")" ::: "memory")
; #define PG8_WAIT_L(n) asm volatile("s_waitcnt lgkmcnt(" #n ")" ::: "memory")
; #define PG8_BAR __builtin_amdgcn_s_barrier()
; #define PG8_SCHED __builtin_amdgcn_sched_barrier(0)
; template <class Epi>
; __device__ __forceinline__ void gemm_phase(LAS unsigned char* lds, const Gemm g, const StaticOrder& S, const Epi& E, const float* SS) {
;     ...
;             PG8_WAIT_V(8); PG8_WAIT_L(0); PG8_BAR; PG8_MMA(1, 0, At, B0); PG8_MMA(1, 1, At, B1); PG8_BAR; PG8_SCHED;
;             PG8_LDB(B0, 1, 0); PG8_LDB(B1, 1, 1); PG8_SCHED; PG8_LDA(At, 1, 0); PG8_STAGE(PG8_SA(0, 1), a2 + hstep, voffA);
;             PG8_WAIT_V(8); PG8_WAIT_L(0); PG8_BAR; PG8_MMA(0, 0, At, B0); PG8_MMA(0, 1, At, B1); PG8_BAR; PG8_SCHED;
;             PG8_LDA(At, 1, 1); PG8_STAGE(PG8_SB(1, 0), b3, voffB); PG8_STAGE(PG8_SB(1, 1), b3 + hstep, voffB); PG8_STAGE(PG8_SA(1, 0), a3, voffA);
	s_nop 0
	v_mfma_f32_16x16x32_bf16 v[30:33], v[134:137], v[190:193], v[30:33]
	v_mfma_f32_16x16x32_bf16 v[26:29], v[154:157], v[190:193], v[26:29]
	v_mfma_f32_16x16x32_bf16 v[22:25], v[134:137], v[200:203], v[22:25]
	v_mfma_f32_16x16x32_bf16 v[18:21], v[154:157], v[200:203], v[18:21]
	v_mfma_f32_16x16x32_bf16 v[14:17], v[134:137], v[216:219], v[14:17]
	v_mfma_f32_16x16x32_bf16 v[10:13], v[154:157], v[216:219], v[10:13]
	v_mfma_f32_16x16x32_bf16 v[6:9], v[134:137], v[224:227], v[6:9]
	v_mfma_f32_16x16x32_bf16 v[2:5], v[154:157], v[224:227], v[2:5]
	v_mfma_f32_16x16x32_bf16 v[30:33], v[150:153], v[194:197], v[30:33]
	v_mfma_f32_16x16x32_bf16 v[26:29], v[158:161], v[194:197], v[26:29]
	v_mfma_f32_16x16x32_bf16 v[22:25], v[150:153], v[204:207], v[22:25]
	v_mfma_f32_16x16x32_bf16 v[18:21], v[158:161], v[204:207], v[18:21]
	v_mfma_f32_16x16x32_bf16 v[14:17], v[150:153], v[220:223], v[14:17]
	v_mfma_f32_16x16x32_bf16 v[10:13], v[158:161], v[220:223], v[10:13]
	v_mfma_f32_16x16x32_bf16 v[6:9], v[150:153], v[228:231], v[6:9]
	v_mfma_f32_16x16x32_bf16 v[2:5], v[158:161], v[228:231], v[2:5]
	v_mfma_f32_16x16x32_bf16 v[98:101], v[162:165], v[190:193], v[98:101]
	v_mfma_f32_16x16x32_bf16 v[102:105], v[182:185], v[190:193], v[102:105]
	v_mfma_f32_16x16x32_bf16 v[106:109], v[162:165], v[200:203], v[106:109]
	v_mfma_f32_16x16x32_bf16 v[110:113], v[182:185], v[200:203], v[110:113]
	v_mfma_f32_16x16x32_bf16 v[114:117], v[162:165], v[216:219], v[114:117]
	v_mfma_f32_16x16x32_bf16 v[118:121], v[182:185], v[216:219], v[118:121]
	v_mfma_f32_16x16x32_bf16 v[122:125], v[162:165], v[224:227], v[122:125]
	v_mfma_f32_16x16x32_bf16 v[126:129], v[182:185], v[224:227], v[126:129]
	v_mfma_f32_16x16x32_bf16 v[98:101], v[178:181], v[194:197], v[98:101]
	v_mfma_f32_16x16x32_bf16 v[102:105], v[186:189], v[194:197], v[102:105]
	v_mfma_f32_16x16x32_bf16 v[106:109], v[178:181], v[204:207], v[106:109]
	v_mfma_f32_16x16x32_bf16 v[110:113], v[186:189], v[204:207], v[110:113]
	v_mfma_f32_16x16x32_bf16 v[114:117], v[178:181], v[220:223], v[114:117]
	v_mfma_f32_16x16x32_bf16 v[118:121], v[186:189], v[220:223], v[118:121]
	v_mfma_f32_16x16x32_bf16 v[122:125], v[178:181], v[228:231], v[122:125]
	v_mfma_f32_16x16x32_bf16 v[126:129], v[186:189], v[228:231], v[126:129]
	s_barrier
	s_add_i32 s6, 0, 0x18000
	v_add_u32_e32 v0, s6, v167
	s_add_i32 s86, 0, 0x1c000
	ds_read_b128 v[134:137], v0
	ds_read_b128 v[150:153], v0 offset:1024
	ds_read_b128 v[154:157], v0 offset:2048
	ds_read_b128 v[158:161], v0 offset:3072
	v_add_u32_e32 v0, s86, v167
	ds_read_b128 v[162:165], v0
	ds_read_b128 v[178:181], v0 offset:1024
	ds_read_b128 v[182:185], v0 offset:2048
	ds_read_b128 v[186:189], v0 offset:3072
	s_add_u32 s68, s68, 0x40000
	s_addc_u32 s69, s69, 0
	s_mov_b32 m0, s14
	v_lshl_add_u64 v[240:241], s[68:69], 0, v[138:139]
	ds_read_b128 v[190:193], v177 offset:32768
	ds_read_b128 v[194:197], v177 offset:33792
	ds_read_b128 v[200:203], v177 offset:34816
	ds_read_b128 v[204:207], v177 offset:35840
	ds_read_b128 v[216:219], v177 offset:36864
	ds_read_b128 v[220:223], v177 offset:37888
	ds_read_b128 v[224:227], v177 offset:38912
	ds_read_b128 v[228:231], v177 offset:39936
	global_load_lds_dwordx4 v[240:241], off
	v_lshl_add_u64 v[240:241], s[68:69], 0, v[142:143]
	s_mov_b32 m0, s15
	s_nop 0
	global_load_lds_dwordx4 v[240:241], off
	s_waitcnt vmcnt(8)
	s_waitcnt lgkmcnt(0)
	s_barrier
	s_nop 0
	v_mfma_f32_16x16x32_bf16 v[94:97], v[134:137], v[190:193], v[94:97]
	v_mfma_f32_16x16x32_bf16 v[90:93], v[154:157], v[190:193], v[90:93]
	v_mfma_f32_16x16x32_bf16 v[86:89], v[134:137], v[200:203], v[86:89]
	v_mfma_f32_16x16x32_bf16 v[82:85], v[154:157], v[200:203], v[82:85]
	v_mfma_f32_16x16x32_bf16 v[78:81], v[134:137], v[216:219], v[78:81]
	v_mfma_f32_16x16x32_bf16 v[74:77], v[154:157], v[216:219], v[74:77]
	v_mfma_f32_16x16x32_bf16 v[70:73], v[134:137], v[224:227], v[70:73]
	v_mfma_f32_16x16x32_bf16 v[66:69], v[154:157], v[224:227], v[66:69]
	v_mfma_f32_16x16x32_bf16 v[94:97], v[150:153], v[194:197], v[94:97]
	v_mfma_f32_16x16x32_bf16 v[90:93], v[158:161], v[194:197], v[90:93]
	v_mfma_f32_16x16x32_bf16 v[86:89], v[150:153], v[204:207], v[86:89]
	v_mfma_f32_16x16x32_bf16 v[82:85], v[158:161], v[204:207], v[82:85]
	v_mfma_f32_16x16x32_bf16 v[78:81], v[150:153], v[220:223], v[78:81]
	v_mfma_f32_16x16x32_bf16 v[74:77], v[158:161], v[220:223], v[74:77]
	v_mfma_f32_16x16x32_bf16 v[70:73], v[150:153], v[228:231], v[70:73]
	v_mfma_f32_16x16x32_bf16 v[66:69], v[158:161], v[228:231], v[66:69]
	v_mfma_f32_16x16x32_bf16 v[62:65], v[162:165], v[190:193], v[62:65]
	v_mfma_f32_16x16x32_bf16 v[58:61], v[182:185], v[190:193], v[58:61]
	v_mfma_f32_16x16x32_bf16 v[54:57], v[162:165], v[200:203], v[54:57]
	v_mfma_f32_16x16x32_bf16 v[50:53], v[182:185], v[200:203], v[50:53]
	v_mfma_f32_16x16x32_bf16 v[46:49], v[162:165], v[216:219], v[46:49]
	v_mfma_f32_16x16x32_bf16 v[42:45], v[182:185], v[216:219], v[42:45]
	v_mfma_f32_16x16x32_bf16 v[38:41], v[162:165], v[224:227], v[38:41]
	v_mfma_f32_16x16x32_bf16 v[34:37], v[182:185], v[224:227], v[34:37]
	v_mfma_f32_16x16x32_bf16 v[62:65], v[178:181], v[194:197], v[62:65]
	v_mfma_f32_16x16x32_bf16 v[58:61], v[186:189], v[194:197], v[58:61]
	v_mfma_f32_16x16x32_bf16 v[54:57], v[178:181], v[204:207], v[54:57]
	v_mfma_f32_16x16x32_bf16 v[50:53], v[186:189], v[204:207], v[50:53]
	v_mfma_f32_16x16x32_bf16 v[46:49], v[178:181], v[220:223], v[46:49]
	v_mfma_f32_16x16x32_bf16 v[42:45], v[186:189], v[220:223], v[42:45]
	v_mfma_f32_16x16x32_bf16 v[38:41], v[178:181], v[228:231], v[38:41]
	v_mfma_f32_16x16x32_bf16 v[34:37], v[186:189], v[228:231], v[34:37]
	s_barrier
; #define PG8_STAGE(bufoff, gbase, voff) do { _Pragma("unroll") for (int _i = 0; _i < 2; ++_i) \
;         __builtin_amdgcn_global_load_lds((const unsigned*)((const char*)(gbase) + (voff)[_i]), (LAS unsigned*)(lds + (bufoff) + ldsw + _i * 8192), 16, 0, 0); } while (0)
; #define PG8_LDA(dst, b, h) do { _Pragma("unroll") for (int m = 0; m < 4; ++m) _Pragma("unroll") for (int k = 0; k < 2; ++k) dst[m][k] = *(const LAS bf16x8*)(lds + PG8_SA(b, h) + aoff + m * 2048 + k * 1024); } while (0)
; #define PG8_MMA(ai, bj, At, Bt) do { __builtin_amdgcn_s_setprio(1); _Pragma("unroll") for (int m = 0; m < 4; ++m) _Pragma("unroll") for (int n = 0; n < 2; ++n) _Pragma("unroll") for (int k = 0; k < 2; ++k) \
;         acc[ai][bj][m][n] = __builtin_amdgcn_mfma_f32_16x16x32_bf16(Bt[n][k], At[m][k], acc[ai][bj][m][n], 0, 0, 0); __builtin_amdgcn_s_setprio(0); } while (0)
; #define PG8_WAIT_V(n) asm volatile("s_waitcnt vmcnt(" #n ")" ::: "memory")
; #define PG8_WAIT_L(n) asm volatile("s_waitcnt lgkmcnt(" #n ")" ::: "memory")
; #define PG8_BAR __builtin_amdgcn_s_barrier()
; #define PG8_SCHED __builtin_amdgcn_sched_barrier(0)
; template <class Epi>
; __device__ __forceinline__ void gemm_phase(LAS unsigned char* lds, const Gemm g, const StaticOrder& S, const Epi& E, const float* SS) {
;     ...
;             PG8_LDA(At, 1, 1); PG8_STAGE(PG8_SB(1, 0), b3, voffB); PG8_STAGE(PG8_SB(1, 1), b3 + hstep, voffB); PG8_STAGE(PG8_SA(1, 0), a3, voffA);
;             PG8_WAIT_V(8); PG8_WAIT_L(0); PG8_BAR; PG8_MMA(1, 0, At, B0); PG8_MMA(1, 1, At, B1); PG8_BAR; PG8_SCHED;
;         }
;         if (wr == 0) PG8_BAR;
	s_add_i32 s6, s6, s25
	v_lshl_add_u64 v[232:233], v[232:233], 0, s[64:65]
	s_mov_b32 m0, s6
	ds_read_b128 v[190:193], v177 offset:49152
	ds_read_b128 v[194:197], v177 offset:50176
	ds_read_b128 v[200:203], v177 offset:51200
	ds_read_b128 v[204:207], v177 offset:52224
	ds_read_b128 v[216:219], v177 offset:53248
	ds_read_b128 v[220:223], v177 offset:54272
	ds_read_b128 v[224:227], v177 offset:55296
	ds_read_b128 v[228:231], v177 offset:56320
	global_load_lds_dwordx4 v[232:233], off
	s_add_i32 m0, s6, 0x2000
	s_add_u32 s60, s60, 0x40080
	v_lshl_add_u64 v[232:233], v[234:235], 0, s[64:65]
	s_addc_u32 s61, s61, 0
	s_add_i32 s6, s86, s25
	global_load_lds_dwordx4 v[232:233], off
	v_lshl_add_u64 v[232:233], s[60:61], 0, v[140:141]
	s_mov_b32 m0, s6
	s_nop 0
	global_load_lds_dwordx4 v[232:233], off
	v_lshl_add_u64 v[232:233], s[60:61], 0, v[144:145]
	s_add_i32 m0, s6, 0x2000
	s_nop 0
	global_load_lds_dwordx4 v[232:233], off
	v_lshl_add_u64 v[232:233], v[236:237], 0, s[64:65]
	s_mov_b32 m0, s89
	s_nop 0
	global_load_lds_dwordx4 v[232:233], off
	v_lshl_add_u64 v[232:233], v[238:239], 0, s[64:65]
	s_mov_b32 m0, s88
	s_nop 0
	global_load_lds_dwordx4 v[232:233], off
	s_waitcnt vmcnt(8)
	s_waitcnt lgkmcnt(0)
	s_barrier
	s_nop 0
	v_mfma_f32_16x16x32_bf16 v[30:33], v[134:137], v[190:193], v[30:33]
	v_mfma_f32_16x16x32_bf16 v[26:29], v[154:157], v[190:193], v[26:29]
	v_mfma_f32_16x16x32_bf16 v[22:25], v[134:137], v[200:203], v[22:25]
	v_mfma_f32_16x16x32_bf16 v[18:21], v[154:157], v[200:203], v[18:21]
	v_mfma_f32_16x16x32_bf16 v[14:17], v[134:137], v[216:219], v[14:17]
	v_mfma_f32_16x16x32_bf16 v[10:13], v[154:157], v[216:219], v[10:13]
	v_mfma_f32_16x16x32_bf16 v[6:9], v[134:137], v[224:227], v[6:9]
	v_mfma_f32_16x16x32_bf16 v[2:5], v[154:157], v[224:227], v[2:5]
	v_mfma_f32_16x16x32_bf16 v[30:33], v[150:153], v[194:197], v[30:33]
	v_mfma_f32_16x16x32_bf16 v[26:29], v[158:161], v[194:197], v[26:29]
	v_mfma_f32_16x16x32_bf16 v[22:25], v[150:153], v[204:207], v[22:25]
	v_mfma_f32_16x16x32_bf16 v[18:21], v[158:161], v[204:207], v[18:21]
	v_mfma_f32_16x16x32_bf16 v[14:17], v[150:153], v[220:223], v[14:17]
	v_mfma_f32_16x16x32_bf16 v[10:13], v[158:161], v[220:223], v[10:13]
	v_mfma_f32_16x16x32_bf16 v[6:9], v[150:153], v[228:231], v[6:9]
	v_mfma_f32_16x16x32_bf16 v[2:5], v[158:161], v[228:231], v[2:5]
	v_mfma_f32_16x16x32_bf16 v[98:101], v[162:165], v[190:193], v[98:101]
	v_mfma_f32_16x16x32_bf16 v[102:105], v[182:185], v[190:193], v[102:105]
	v_mfma_f32_16x16x32_bf16 v[106:109], v[162:165], v[200:203], v[106:109]
	v_mfma_f32_16x16x32_bf16 v[110:113], v[182:185], v[200:203], v[110:113]
	v_mfma_f32_16x16x32_bf16 v[114:117], v[162:165], v[216:219], v[114:117]
	v_mfma_f32_16x16x32_bf16 v[118:121], v[182:185], v[216:219], v[118:121]
	v_mfma_f32_16x16x32_bf16 v[122:125], v[162:165], v[224:227], v[122:125]
	v_mfma_f32_16x16x32_bf16 v[126:129], v[182:185], v[224:227], v[126:129]
	v_mfma_f32_16x16x32_bf16 v[98:101], v[178:181], v[194:197], v[98:101]
	v_mfma_f32_16x16x32_bf16 v[102:105], v[186:189], v[194:197], v[102:105]
	v_mfma_f32_16x16x32_bf16 v[106:109], v[178:181], v[204:207], v[106:109]
	v_mfma_f32_16x16x32_bf16 v[110:113], v[186:189], v[204:207], v[110:113]
	v_mfma_f32_16x16x32_bf16 v[114:117], v[178:181], v[220:223], v[114:117]
	v_mfma_f32_16x16x32_bf16 v[118:121], v[186:189], v[220:223], v[118:121]
	v_mfma_f32_16x16x32_bf16 v[122:125], v[178:181], v[228:231], v[122:125]
	v_mfma_f32_16x16x32_bf16 v[126:129], v[186:189], v[228:231], v[126:129]
	s_barrier
	s_add_i32 vcc_lo, vcc_lo, 2
	s_add_u32 s58, s58, 0x100
	s_addc_u32 s59, s59, 0
	s_cmp_gt_u32 vcc_lo, 13
	s_cbranch_scc0 .LBB0_501
	s_and_b64 vcc, exec, s[44:45]
	s_cbranch_vccz .LBB0_504
	s_barrier

; #define PG8_STAGE(bufoff, gbase, voff) do { _Pragma("unroll") for (int _i = 0; _i < 2; ++_i) \
;         __builtin_amdgcn_global_load_lds((const unsigned*)((const char*)(gbase) + (voff)[_i]), (LAS unsigned*)(lds + (bufoff) + ldsw + _i * 8192), 16, 0, 0); } while (0)
; #define PG8_LDA(dst, b, h) do { _Pragma("unroll") for (int m = 0; m < 4; ++m) _Pragma("unroll") for (int k = 0; k < 2; ++k) dst[m][k] = *(const LAS bf16x8*)(lds + PG8_SA(b, h) + aoff + m * 2048 + k * 1024); } while (0)
; #define PG8_LDB(dst, b, h) do { _Pragma("unroll") for (int n = 0; n < 2; ++n) _Pragma("unroll") for (int k = 0; k < 2; ++k) dst[n][k] = *(const LAS bf16x8*)(lds + PG8_SB(b, h) + boff + n * 2048 + k * 1024); } while (0)
; #define PG8_MMA(ai, bj, At, Bt) do { __builtin_amdgcn_s_setprio(1); _Pragma("unroll") for (int m = 0; m < 4; ++m) _Pragma("unroll") for (int n = 0; n < 2; ++n) _Pragma("unroll") for (int k = 0; k < 2; ++k) \
;         acc[ai][bj][m][n] = __builtin_amdgcn_mfma_f32_16x16x32_bf16(Bt[n][k], At[m][k], acc[ai][bj][m][n], 0, 0, 0); __builtin_amdgcn_s_setprio(0); } while (0)
; #define PG8_WAIT_V(n) asm volatile("s_waitcnt vmcnt(" #n ")" ::: "memory")
; #define PG8_WAIT_L(n) asm volatile("s_waitcnt lgkmcnt(" #n ")" ::: "memory")
; #define PG8_BAR __builtin_amdgcn_s_barrier()
; #define PG8_SCHED __builtin_amdgcn_sched_barrier(0)
; template <class Epi>
; __device__ __forceinline__ void gemm_phase(LAS unsigned char* lds, const Gemm g, const StaticOrder& S, const Epi& E, const float* SS) {
;     ...
;         for (int t = 0; t < nt; t += 2) {
;             const bool last = (t == nt - 2);
;             const char* a1 = cA + (size_t)(t + 1) * kstep;
;             const char* a2 = last ? nA : cA + (size_t)(t + 2) * kstep; const char* b2 = last ? nB : cB + (size_t)(t + 2) * kstep;
;             const char* a3 = a2 + kstep; const char* b3 = b2 + kstep;
;             PG8_LDB(B0, 0, 0); PG8_LDB(B1, 0, 1); PG8_SCHED; PG8_LDA(At, 0, 0); PG8_STAGE(PG8_SA(1, 1), a1 + hstep, voffA);
;             PG8_WAIT_V(8); PG8_WAIT_L(0); PG8_BAR; PG8_MMA(0, 0, At, B0); PG8_MMA(0, 1, At, B1); PG8_BAR; PG8_SCHED;
;             PG8_LDA(At, 0, 1); PG8_STAGE(PG8_SB(0, 0), b2, voffB); PG8_STAGE(PG8_SB(0, 1), b2 + hstep, voffB); PG8_STAGE(PG8_SA(0, 0), a2, voffA);
;             PG8_WAIT_V(8); PG8_WAIT_L(0); PG8_BAR; PG8_MMA(1, 0, At, B0); PG8_MMA(1, 1, At, B1); PG8_BAR; PG8_SCHED;
.LBB0_640:
	s_add_i32 s68, s44, 2
	s_add_u32 s6, s42, 0x80
	s_addc_u32 s45, s43, 0
	s_add_i32 s69, 0, 0x10000
	s_cmp_eq_u32 s54, s44
	s_cselect_b32 s45, s5, s45
	s_cselect_b32 s44, s4, s6
	s_cselect_b32 s87, s41, s61
	s_cselect_b32 s86, s40, s60
	s_add_i32 s6, 0, 0x14000
	v_add_u32_e32 v126, s69, v230
	v_add_u32_e32 v150, s6, v230
	ds_read_b128 v[106:109], v126
	ds_read_b128 v[110:113], v126 offset:1024
	ds_read_b128 v[122:125], v126 offset:2048
	ds_read_b128 v[126:129], v126 offset:3072
	ds_read_b128 v[138:141], v150
	ds_read_b128 v[142:145], v150 offset:1024
	ds_read_b128 v[146:149], v150 offset:2048
	ds_read_b128 v[150:153], v150 offset:3072
	v_lshl_add_u64 v[216:217], s[42:43], 0, v[202:203]
	s_add_i32 m0, s16, 0xc000
	ds_read_b128 v[162:165], v231
	ds_read_b128 v[166:169], v231 offset:1024
	ds_read_b128 v[170:173], v231 offset:2048
	ds_read_b128 v[174:177], v231 offset:3072
	ds_read_b128 v[178:181], v231 offset:4096
	ds_read_b128 v[182:185], v231 offset:5120
	ds_read_b128 v[186:189], v231 offset:6144
	ds_read_b128 v[204:207], v231 offset:7168
	global_load_lds_dwordx4 v[216:217], off
	v_lshl_add_u64 v[216:217], s[42:43], 0, v[200:201]
	s_add_i32 m0, s16, 0xe000
	s_nop 0
	global_load_lds_dwordx4 v[216:217], off
	s_waitcnt vmcnt(8)
	s_waitcnt lgkmcnt(0)
	s_barrier
	s_nop 0
	v_mfma_f32_16x16x32_bf16 v[158:161], v[106:109], v[162:165], v[158:161]
	v_mfma_f32_16x16x32_bf16 v[154:157], v[122:125], v[162:165], v[154:157]
	v_mfma_f32_16x16x32_bf16 v[118:121], v[106:109], v[170:173], v[118:121]
	v_mfma_f32_16x16x32_bf16 v[114:117], v[122:125], v[170:173], v[114:117]
	v_mfma_f32_16x16x32_bf16 v[94:97], v[106:109], v[178:181], v[94:97]
	v_mfma_f32_16x16x32_bf16 v[90:93], v[122:125], v[178:181], v[90:93]
	v_mfma_f32_16x16x32_bf16 v[78:81], v[106:109], v[186:189], v[78:81]
	v_mfma_f32_16x16x32_bf16 v[74:77], v[122:125], v[186:189], v[74:77]
	v_mfma_f32_16x16x32_bf16 v[158:161], v[110:113], v[166:169], v[158:161]
	v_mfma_f32_16x16x32_bf16 v[154:157], v[126:129], v[166:169], v[154:157]
	v_mfma_f32_16x16x32_bf16 v[118:121], v[110:113], v[174:177], v[118:121]
	v_mfma_f32_16x16x32_bf16 v[114:117], v[126:129], v[174:177], v[114:117]
	v_mfma_f32_16x16x32_bf16 v[94:97], v[110:113], v[182:185], v[94:97]
	v_mfma_f32_16x16x32_bf16 v[90:93], v[126:129], v[182:185], v[90:93]
	v_mfma_f32_16x16x32_bf16 v[78:81], v[110:113], v[204:207], v[78:81]
	v_mfma_f32_16x16x32_bf16 v[74:77], v[126:129], v[204:207], v[74:77]
	v_mfma_f32_16x16x32_bf16 v[134:137], v[138:141], v[162:165], v[134:137]
	v_mfma_f32_16x16x32_bf16 v[130:133], v[146:149], v[162:165], v[130:133]
	v_mfma_f32_16x16x32_bf16 v[102:105], v[138:141], v[170:173], v[102:105]
	v_mfma_f32_16x16x32_bf16 v[98:101], v[146:149], v[170:173], v[98:101]
	v_mfma_f32_16x16x32_bf16 v[86:89], v[138:141], v[178:181], v[86:89]
	v_mfma_f32_16x16x32_bf16 v[82:85], v[146:149], v[178:181], v[82:85]
	v_mfma_f32_16x16x32_bf16 v[70:73], v[138:141], v[186:189], v[70:73]
	v_mfma_f32_16x16x32_bf16 v[66:69], v[146:149], v[186:189], v[66:69]
	v_mfma_f32_16x16x32_bf16 v[134:137], v[142:145], v[166:169], v[134:137]
	v_mfma_f32_16x16x32_bf16 v[130:133], v[150:153], v[166:169], v[130:133]
	v_mfma_f32_16x16x32_bf16 v[102:105], v[142:145], v[174:177], v[102:105]
	v_mfma_f32_16x16x32_bf16 v[98:101], v[150:153], v[174:177], v[98:101]
	v_mfma_f32_16x16x32_bf16 v[86:89], v[142:145], v[182:185], v[86:89]
	v_mfma_f32_16x16x32_bf16 v[82:85], v[150:153], v[182:185], v[82:85]
	v_mfma_f32_16x16x32_bf16 v[70:73], v[142:145], v[204:207], v[70:73]
	v_mfma_f32_16x16x32_bf16 v[66:69], v[150:153], v[204:207], v[66:69]
	s_barrier
	s_add_i32 s69, s69, s15
	v_lshl_add_u64 v[216:217], s[86:87], 0, v[192:193]
	s_mov_b32 m0, s69
	ds_read_b128 v[162:165], v231 offset:16384
	ds_read_b128 v[166:169], v231 offset:17408
	ds_read_b128 v[170:173], v231 offset:18432
	ds_read_b128 v[174:177], v231 offset:19456
	ds_read_b128 v[178:181], v231 offset:20480
	ds_read_b128 v[182:185], v231 offset:21504
	ds_read_b128 v[186:189], v231 offset:22528
	ds_read_b128 v[204:207], v231 offset:23552
	global_load_lds_dwordx4 v[216:217], off
	s_add_i32 m0, s69, 0x2000
	v_lshl_add_u64 v[218:219], s[86:87], 0, v[196:197]
	s_add_u32 s86, s86, s30
	s_addc_u32 s87, s87, 0
	s_add_i32 s6, s6, s15
	global_load_lds_dwordx4 v[218:219], off
	v_lshl_add_u64 v[220:221], s[86:87], 0, v[192:193]
	s_mov_b32 m0, s6
	v_lshl_add_u64 v[222:223], s[86:87], 0, v[196:197]
	global_load_lds_dwordx4 v[220:221], off
	s_add_i32 m0, s6, 0x2000
	v_lshl_add_u64 v[224:225], s[44:45], 0, v[190:191]
	global_load_lds_dwordx4 v[222:223], off
	s_mov_b32 m0, s16
	v_lshl_add_u64 v[226:227], s[44:45], 0, v[194:195]
	global_load_lds_dwordx4 v[224:225], off
	s_mov_b32 m0, s17
	s_nop 0
	global_load_lds_dwordx4 v[226:227], off
	s_waitcnt vmcnt(8)
	s_waitcnt lgkmcnt(0)
	s_barrier
; #define PG8_STAGE(bufoff, gbase, voff) do { _Pragma("unroll") for (int _i = 0; _i < 2; ++_i) \
;         __builtin_amdgcn_global_load_lds((const unsigned*)((const char*)(gbase) + (voff)[_i]), (LAS unsigned*)(lds + (bufoff) + ldsw + _i * 8192), 16, 0, 0); } while (0)
; #define PG8_LDA(dst, b, h) do { _Pragma("unroll") for (int m = 0; m < 4; ++m) _Pragma("unroll") for (int k = 0; k < 2; ++k) dst[m][k] = *(const LAS bf16x8*)(lds + PG8_SA(b, h) + aoff + m * 2048 + k * 1024); } while (0)
; #define PG8_LDB(dst, b, h) do { _Pragma("unroll") for (int n = 0; n < 2; ++n) _Pragma("unroll") for (int k = 0; k < 2; ++k) dst[n][k] = *(const LAS bf16x8*)(lds + PG8_SB(b, h) + boff + n * 2048 + k * 1024); } while (0)
; #define PG8_MMA(ai, bj, At, Bt) do { __builtin_amdgcn_s_setprio(1); _Pragma("unroll") for (int m = 0; m < 4; ++m) _Pragma("unroll") for (int n = 0; n < 2; ++n) _Pragma("unroll") for (int k = 0; k < 2; ++k) \
;         acc[ai][bj][m][n] = __builtin_amdgcn_mfma_f32_16x16x32_bf16(Bt[n][k], At[m][k], acc[ai][bj][m][n], 0, 0, 0); __builtin_amdgcn_s_setprio(0); } while (0)
; #define PG8_WAIT_V(n) asm volatile("s_waitcnt vmcnt(" #n ")" ::: "memory")
; #define PG8_WAIT_L(n) asm volatile("s_waitcnt lgkmcnt(" #n ")" ::: "memory")
; #define PG8_BAR __builtin_amdgcn_s_barrier()
; #define PG8_SCHED __builtin_amdgcn_sched_barrier(0)
; template <class Epi>
; __device__ __forceinline__ void gemm_phase(LAS unsigned char* lds, const Gemm g, const StaticOrder& S, const Epi& E, const float* SS) {
;     ...
;             PG8_WAIT_V(8); PG8_WAIT_L(0); PG8_BAR; PG8_MMA(1, 0, At, B0); PG8_MMA(1, 1, At, B1); PG8_BAR; PG8_SCHED;
;             PG8_LDB(B0, 1, 0); PG8_LDB(B1, 1, 1); PG8_SCHED; PG8_LDA(At, 1, 0); PG8_STAGE(PG8_SA(0, 1), a2 + hstep, voffA);
;             PG8_WAIT_V(8); PG8_WAIT_L(0); PG8_BAR; PG8_MMA(0, 0, At, B0); PG8_MMA(0, 1, At, B1); PG8_BAR; PG8_SCHED;
;             PG8_LDA(At, 1, 1); PG8_STAGE(PG8_SB(1, 0), b3, voffB); PG8_STAGE(PG8_SB(1, 1), b3 + hstep, voffB); PG8_STAGE(PG8_SA(1, 0), a3, voffA);
	s_nop 0
	v_mfma_f32_16x16x32_bf16 v[62:65], v[106:109], v[162:165], v[62:65]
	v_mfma_f32_16x16x32_bf16 v[58:61], v[122:125], v[162:165], v[58:61]
	v_mfma_f32_16x16x32_bf16 v[46:49], v[106:109], v[170:173], v[46:49]
	v_mfma_f32_16x16x32_bf16 v[42:45], v[122:125], v[170:173], v[42:45]
	v_mfma_f32_16x16x32_bf16 v[30:33], v[106:109], v[178:181], v[30:33]
	v_mfma_f32_16x16x32_bf16 v[26:29], v[122:125], v[178:181], v[26:29]
	v_mfma_f32_16x16x32_bf16 v[14:17], v[106:109], v[186:189], v[14:17]
	v_mfma_f32_16x16x32_bf16 v[10:13], v[122:125], v[186:189], v[10:13]
	v_mfma_f32_16x16x32_bf16 v[62:65], v[110:113], v[166:169], v[62:65]
	v_mfma_f32_16x16x32_bf16 v[58:61], v[126:129], v[166:169], v[58:61]
	v_mfma_f32_16x16x32_bf16 v[46:49], v[110:113], v[174:177], v[46:49]
	v_mfma_f32_16x16x32_bf16 v[42:45], v[126:129], v[174:177], v[42:45]
	v_mfma_f32_16x16x32_bf16 v[30:33], v[110:113], v[182:185], v[30:33]
	v_mfma_f32_16x16x32_bf16 v[26:29], v[126:129], v[182:185], v[26:29]
	v_mfma_f32_16x16x32_bf16 v[14:17], v[110:113], v[204:207], v[14:17]
	v_mfma_f32_16x16x32_bf16 v[10:13], v[126:129], v[204:207], v[10:13]
	v_mfma_f32_16x16x32_bf16 v[54:57], v[138:141], v[162:165], v[54:57]
	v_mfma_f32_16x16x32_bf16 v[50:53], v[146:149], v[162:165], v[50:53]
	v_mfma_f32_16x16x32_bf16 v[38:41], v[138:141], v[170:173], v[38:41]
	v_mfma_f32_16x16x32_bf16 v[34:37], v[146:149], v[170:173], v[34:37]
	v_mfma_f32_16x16x32_bf16 v[22:25], v[138:141], v[178:181], v[22:25]
	v_mfma_f32_16x16x32_bf16 v[18:21], v[146:149], v[178:181], v[18:21]
	v_mfma_f32_16x16x32_bf16 v[6:9], v[138:141], v[186:189], v[6:9]
	v_mfma_f32_16x16x32_bf16 v[2:5], v[146:149], v[186:189], v[2:5]
	v_mfma_f32_16x16x32_bf16 v[54:57], v[142:145], v[166:169], v[54:57]
	v_mfma_f32_16x16x32_bf16 v[50:53], v[150:153], v[166:169], v[50:53]
	v_mfma_f32_16x16x32_bf16 v[38:41], v[142:145], v[174:177], v[38:41]
	v_mfma_f32_16x16x32_bf16 v[34:37], v[150:153], v[174:177], v[34:37]
	v_mfma_f32_16x16x32_bf16 v[22:25], v[142:145], v[182:185], v[22:25]
	v_mfma_f32_16x16x32_bf16 v[18:21], v[150:153], v[182:185], v[18:21]
	v_mfma_f32_16x16x32_bf16 v[6:9], v[142:145], v[204:207], v[6:9]
	v_mfma_f32_16x16x32_bf16 v[2:5], v[150:153], v[204:207], v[2:5]
	s_barrier
	s_add_i32 s6, 0, 0x18000
	s_add_i32 s69, 0, 0x1c000
	v_add_u32_e32 v126, s6, v230
	v_add_u32_e32 v150, s69, v230
	ds_read_b128 v[106:109], v126
	ds_read_b128 v[110:113], v126 offset:1024
	ds_read_b128 v[122:125], v126 offset:2048
	ds_read_b128 v[126:129], v126 offset:3072
	ds_read_b128 v[138:141], v150
	ds_read_b128 v[142:145], v150 offset:1024
	ds_read_b128 v[146:149], v150 offset:2048
	ds_read_b128 v[150:153], v150 offset:3072
	s_add_u32 s44, s44, s30
	s_addc_u32 s45, s45, 0
	s_mov_b32 m0, s48
	v_lshl_add_u64 v[232:233], s[44:45], 0, v[190:191]
	ds_read_b128 v[162:165], v231 offset:32768
	ds_read_b128 v[166:169], v231 offset:33792
	ds_read_b128 v[170:173], v231 offset:34816
	ds_read_b128 v[174:177], v231 offset:35840
	ds_read_b128 v[178:181], v231 offset:36864
	ds_read_b128 v[182:185], v231 offset:37888
	ds_read_b128 v[186:189], v231 offset:38912
	ds_read_b128 v[204:207], v231 offset:39936
	global_load_lds_dwordx4 v[232:233], off
	v_lshl_add_u64 v[232:233], s[44:45], 0, v[194:195]
	s_mov_b32 m0, s49
	s_nop 0
	global_load_lds_dwordx4 v[232:233], off
	s_waitcnt vmcnt(8)
	s_waitcnt lgkmcnt(0)
	s_barrier
	s_nop 0
	v_mfma_f32_16x16x32_bf16 v[158:161], v[106:109], v[162:165], v[158:161]
	v_mfma_f32_16x16x32_bf16 v[154:157], v[122:125], v[162:165], v[154:157]
	v_mfma_f32_16x16x32_bf16 v[118:121], v[106:109], v[170:173], v[118:121]
	v_mfma_f32_16x16x32_bf16 v[114:117], v[122:125], v[170:173], v[114:117]
	v_mfma_f32_16x16x32_bf16 v[94:97], v[106:109], v[178:181], v[94:97]
	v_mfma_f32_16x16x32_bf16 v[90:93], v[122:125], v[178:181], v[90:93]
	v_mfma_f32_16x16x32_bf16 v[78:81], v[106:109], v[186:189], v[78:81]
	v_mfma_f32_16x16x32_bf16 v[74:77], v[122:125], v[186:189], v[74:77]
	v_mfma_f32_16x16x32_bf16 v[158:161], v[110:113], v[166:169], v[158:161]
	v_mfma_f32_16x16x32_bf16 v[154:157], v[126:129], v[166:169], v[154:157]
	v_mfma_f32_16x16x32_bf16 v[118:121], v[110:113], v[174:177], v[118:121]
	v_mfma_f32_16x16x32_bf16 v[114:117], v[126:129], v[174:177], v[114:117]
	v_mfma_f32_16x16x32_bf16 v[94:97], v[110:113], v[182:185], v[94:97]
	v_mfma_f32_16x16x32_bf16 v[90:93], v[126:129], v[182:185], v[90:93]
	v_mfma_f32_16x16x32_bf16 v[78:81], v[110:113], v[204:207], v[78:81]
	v_mfma_f32_16x16x32_bf16 v[74:77], v[126:129], v[204:207], v[74:77]
	v_mfma_f32_16x16x32_bf16 v[134:137], v[138:141], v[162:165], v[134:137]
	v_mfma_f32_16x16x32_bf16 v[130:133], v[146:149], v[162:165], v[130:133]
	v_mfma_f32_16x16x32_bf16 v[102:105], v[138:141], v[170:173], v[102:105]
	v_mfma_f32_16x16x32_bf16 v[98:101], v[146:149], v[170:173], v[98:101]
	v_mfma_f32_16x16x32_bf16 v[86:89], v[138:141], v[178:181], v[86:89]
	v_mfma_f32_16x16x32_bf16 v[82:85], v[146:149], v[178:181], v[82:85]
	v_mfma_f32_16x16x32_bf16 v[70:73], v[138:141], v[186:189], v[70:73]
	v_mfma_f32_16x16x32_bf16 v[66:69], v[146:149], v[186:189], v[66:69]
	v_mfma_f32_16x16x32_bf16 v[134:137], v[142:145], v[166:169], v[134:137]
	v_mfma_f32_16x16x32_bf16 v[130:133], v[150:153], v[166:169], v[130:133]
	v_mfma_f32_16x16x32_bf16 v[102:105], v[142:145], v[174:177], v[102:105]
	v_mfma_f32_16x16x32_bf16 v[98:101], v[150:153], v[174:177], v[98:101]
	v_mfma_f32_16x16x32_bf16 v[86:89], v[142:145], v[182:185], v[86:89]
	v_mfma_f32_16x16x32_bf16 v[82:85], v[150:153], v[182:185], v[82:85]
	v_mfma_f32_16x16x32_bf16 v[70:73], v[142:145], v[204:207], v[70:73]
	v_mfma_f32_16x16x32_bf16 v[66:69], v[150:153], v[204:207], v[66:69]
	s_barrier
; #define PG8_STAGE(bufoff, gbase, voff) do { _Pragma("unroll") for (int _i = 0; _i < 2; ++_i) \
;         __builtin_amdgcn_global_load_lds((const unsigned*)((const char*)(gbase) + (voff)[_i]), (LAS unsigned*)(lds + (bufoff) + ldsw + _i * 8192), 16, 0, 0); } while (0)
; #define PG8_LDA(dst, b, h) do { _Pragma("unroll") for (int m = 0; m < 4; ++m) _Pragma("unroll") for (int k = 0; k < 2; ++k) dst[m][k] = *(const LAS bf16x8*)(lds + PG8_SA(b, h) + aoff + m * 2048 + k * 1024); } while (0)
; #define PG8_MMA(ai, bj, At, Bt) do { __builtin_amdgcn_s_setprio(1); _Pragma("unroll") for (int m = 0; m < 4; ++m) _Pragma("unroll") for (int n = 0; n < 2; ++n) _Pragma("unroll") for (int k = 0; k < 2; ++k) \
;         acc[ai][bj][m][n] = __builtin_amdgcn_mfma_f32_16x16x32_bf16(Bt[n][k], At[m][k], acc[ai][bj][m][n], 0, 0, 0); __builtin_amdgcn_s_setprio(0); } while (0)
; #define PG8_WAIT_V(n) asm volatile("s_waitcnt vmcnt(" #n ")" ::: "memory")
; #define PG8_WAIT_L(n) asm volatile("s_waitcnt lgkmcnt(" #n ")" ::: "memory")
; #define PG8_BAR __builtin_amdgcn_s_barrier()
; #define PG8_SCHED __builtin_amdgcn_sched_barrier(0)
; template <class Epi>
; __device__ __forceinline__ void gemm_phase(LAS unsigned char* lds, const Gemm g, const StaticOrder& S, const Epi& E, const float* SS) {
;     ...
;             PG8_LDA(At, 1, 1); PG8_STAGE(PG8_SB(1, 0), b3, voffB); PG8_STAGE(PG8_SB(1, 1), b3 + hstep, voffB); PG8_STAGE(PG8_SA(1, 0), a3, voffA);
;             PG8_WAIT_V(8); PG8_WAIT_L(0); PG8_BAR; PG8_MMA(1, 0, At, B0); PG8_MMA(1, 1, At, B1); PG8_BAR; PG8_SCHED;
;         }
;         if (wr == 0) PG8_BAR;
	s_add_i32 s6, s6, s15
	v_lshl_add_u64 v[216:217], v[216:217], 0, s[64:65]
	s_mov_b32 m0, s6
	ds_read_b128 v[162:165], v231 offset:49152
	ds_read_b128 v[166:169], v231 offset:50176
	ds_read_b128 v[170:173], v231 offset:51200
	ds_read_b128 v[174:177], v231 offset:52224
	ds_read_b128 v[178:181], v231 offset:53248
	ds_read_b128 v[182:185], v231 offset:54272
	ds_read_b128 v[186:189], v231 offset:55296
	ds_read_b128 v[204:207], v231 offset:56320
	global_load_lds_dwordx4 v[216:217], off
	v_lshl_add_u64 v[216:217], v[218:219], 0, s[64:65]
	s_add_i32 m0, s6, 0x2000
	s_add_i32 s6, s69, s15
	global_load_lds_dwordx4 v[216:217], off
	v_lshl_add_u64 v[216:217], v[220:221], 0, s[64:65]
	s_mov_b32 m0, s6
	s_nop 0
	global_load_lds_dwordx4 v[216:217], off
	v_lshl_add_u64 v[216:217], v[222:223], 0, s[64:65]
	s_add_i32 m0, s6, 0x2000
	s_nop 0
	global_load_lds_dwordx4 v[216:217], off
	v_lshl_add_u64 v[216:217], v[224:225], 0, s[64:65]
	s_mov_b32 m0, s50
	s_nop 0
	global_load_lds_dwordx4 v[216:217], off
	v_lshl_add_u64 v[216:217], v[226:227], 0, s[64:65]
	s_mov_b32 m0, s51
	s_nop 0
	global_load_lds_dwordx4 v[216:217], off
	s_waitcnt vmcnt(8)
	s_waitcnt lgkmcnt(0)
	s_barrier
	s_nop 0
	v_mfma_f32_16x16x32_bf16 v[62:65], v[106:109], v[162:165], v[62:65]
	v_mfma_f32_16x16x32_bf16 v[58:61], v[122:125], v[162:165], v[58:61]
	v_mfma_f32_16x16x32_bf16 v[46:49], v[106:109], v[170:173], v[46:49]
	v_mfma_f32_16x16x32_bf16 v[42:45], v[122:125], v[170:173], v[42:45]
	v_mfma_f32_16x16x32_bf16 v[30:33], v[106:109], v[178:181], v[30:33]
	v_mfma_f32_16x16x32_bf16 v[26:29], v[122:125], v[178:181], v[26:29]
	v_mfma_f32_16x16x32_bf16 v[14:17], v[106:109], v[186:189], v[14:17]
	v_mfma_f32_16x16x32_bf16 v[10:13], v[122:125], v[186:189], v[10:13]
	v_mfma_f32_16x16x32_bf16 v[62:65], v[110:113], v[166:169], v[62:65]
	v_mfma_f32_16x16x32_bf16 v[58:61], v[126:129], v[166:169], v[58:61]
	v_mfma_f32_16x16x32_bf16 v[46:49], v[110:113], v[174:177], v[46:49]
	v_mfma_f32_16x16x32_bf16 v[42:45], v[126:129], v[174:177], v[42:45]
	v_mfma_f32_16x16x32_bf16 v[30:33], v[110:113], v[182:185], v[30:33]
	v_mfma_f32_16x16x32_bf16 v[26:29], v[126:129], v[182:185], v[26:29]
	v_mfma_f32_16x16x32_bf16 v[14:17], v[110:113], v[204:207], v[14:17]
	v_mfma_f32_16x16x32_bf16 v[10:13], v[126:129], v[204:207], v[10:13]
	v_mfma_f32_16x16x32_bf16 v[54:57], v[138:141], v[162:165], v[54:57]
	v_mfma_f32_16x16x32_bf16 v[50:53], v[146:149], v[162:165], v[50:53]
	v_mfma_f32_16x16x32_bf16 v[38:41], v[138:141], v[170:173], v[38:41]
	v_mfma_f32_16x16x32_bf16 v[34:37], v[146:149], v[170:173], v[34:37]
	v_mfma_f32_16x16x32_bf16 v[22:25], v[138:141], v[178:181], v[22:25]
	v_mfma_f32_16x16x32_bf16 v[18:21], v[146:149], v[178:181], v[18:21]
	v_mfma_f32_16x16x32_bf16 v[6:9], v[138:141], v[186:189], v[6:9]
	v_mfma_f32_16x16x32_bf16 v[2:5], v[146:149], v[186:189], v[2:5]
	v_mfma_f32_16x16x32_bf16 v[54:57], v[142:145], v[166:169], v[54:57]
	v_mfma_f32_16x16x32_bf16 v[50:53], v[150:153], v[166:169], v[50:53]
	v_mfma_f32_16x16x32_bf16 v[38:41], v[142:145], v[174:177], v[38:41]
	v_mfma_f32_16x16x32_bf16 v[34:37], v[150:153], v[174:177], v[34:37]
	v_mfma_f32_16x16x32_bf16 v[22:25], v[142:145], v[182:185], v[22:25]
	v_mfma_f32_16x16x32_bf16 v[18:21], v[150:153], v[182:185], v[18:21]
	v_mfma_f32_16x16x32_bf16 v[6:9], v[142:145], v[204:207], v[6:9]
	v_mfma_f32_16x16x32_bf16 v[2:5], v[150:153], v[204:207], v[2:5]
	s_barrier
	s_add_u32 s60, s60, 0x100
	s_addc_u32 s61, s61, 0
	s_add_u32 s42, s42, 0x100
	s_addc_u32 s43, s43, 0
	s_cmp_ge_u32 s68, s53
	s_mov_b32 s44, s68
	s_cbranch_scc0 .LBB0_640
	s_and_b64 vcc, exec, s[36:37]
	s_cbranch_vccz .LBB0_643
	s_barrier
